# neighbourhood attention: K fragment LDS reads of each key half hoisted into spare registers with counted waits
# baseline (speedup 1.0000x reference)
; template <bool NA, bool FIXED> ...
;     ...
; #pragma unroll
;       for (int ks = 0; ks < 4; ++ks) {
;         bf16x8 ak = *(const bf16x8*)(sk + s2 * 4096 + koff + (((ks * 2 + hl) ^ swk) << 4));
;         sc = __builtin_amdgcn_mfma_f32_32x32x16_bf16(ak, bq[ks], sc, 0, 0, 0);
;       }
;       const bool na_far = NA && latent && (s2 != (qcol0 >> 5));
;       if (na_far) {
;         const float* brow_ = btab + (tile - r + 7) * 31;
;         const int kcb = s2 * 32 + hl * 4;
;         if (qcol0 == 0) na_softmax<0, 4>(sc, o0, o1, mrun, lsum, brow_, kcb, w0, qcol, cs, lane);
;         else na_softmax<12, 16>(sc, o0, o1, mrun, lsum, brow_, kcb, w0, qcol, cs, lane);
;       } else {
;       if (!FIXED) {
;       float tmax;
;       if (NA && latent) {
;         const float* brow_ = btab + (tile - r + 7) * 31;
;         const int kcb = s2 * 32 + hl * 4;
; #pragma unroll
;         for (int i = 0; i < 16; ++i) {
;           int kc = kcb + 8 * (i >> 2) + (i & 3);
;           bool valid = (kc >= w0) && (kc < w0 + 16);
;           int dx = min(max(kc - qcol, -15), 15) + 15;
;           float bv = brow_[dx];
;           sc[i] = valid ? sc[i] * cs + bv : -1e30f;
;         }
;         tmax = fmaxf(fmaxf(sc[0], sc[1]), fmaxf(sc[2], sc[3]));
; #pragma unroll
;         for (int i = 4; i < 16; i += 4) tmax = fmaxf(tmax, fmaxf(fmaxf(sc[i], sc[i + 1]), fmaxf(sc[i + 2], sc[i + 3])));
;       } else {
;         tmax = fmaxf(fmaxf(sc[0], sc[1]), fmaxf(sc[2], sc[3]));
; #pragma unroll
;         for (int i = 4; i < 16; i += 4) tmax = fmaxf(tmax, fmaxf(fmaxf(sc[i], sc[i + 1]), fmaxf(sc[i + 2], sc[i + 3])));
;         tmax *= cs;
.LBB0_350:
	s_add_i32 s25, s25, 20
	s_and_b64 s[92:93], s[16:17], exec
	s_cselect_b32 s46, s46, s25
	s_and_b32 s25, s44, 0xc000
	s_add_i32 s47, s25, 0
	v_add_u32_e32 v0, s47, v137
	v_add_u32_e32 v201, v0, v139
	ds_read_b128 v[2:5], v201
	v_add_u32_e32 v198, v0, v140
	ds_read_b128 v[6:9], v198
	v_add_u32_e32 v200, v0, v141
	v_add_u32_e32 v199, v0, v142
	ds_read_b128 v[204:207], v200
	ds_read_b128 v[208:211], v199
	v_readlane_b32 s92, v252, 5
	v_readlane_b32 s93, v252, 6
	s_and_b64 s[92:93], s[92:93], s[16:17]
	s_waitcnt lgkmcnt(3)
	v_mfma_f32_32x32x16_bf16 v[80:95], v[2:5], v[112:115], 0
	s_mov_b32 s25, s24
	s_andn2_b64 vcc, exec, s[92:93]
	s_mov_b64 s[92:93], -1
	s_waitcnt lgkmcnt(2)
	v_mfma_f32_32x32x16_bf16 v[80:95], v[6:9], v[116:119], v[80:95]
	s_waitcnt lgkmcnt(1)
	v_mfma_f32_32x32x16_bf16 v[80:95], v[204:207], v[120:123], v[80:95]
	s_waitcnt lgkmcnt(0)
	v_mfma_f32_32x32x16_bf16 v[80:95], v[208:211], v[124:127], v[80:95]
	s_cbranch_vccz .LBB0_390
	s_and_b64 vcc, exec, s[96:97]
	s_cbranch_vccz .LBB0_353
	s_nop 8
	v_max_f32_e32 v0, v81, v81
	v_max_f32_e32 v2, v80, v80
	v_max_f32_e32 v0, v2, v0
	v_max_f32_e32 v2, v83, v83
	v_max_f32_e32 v3, v82, v82
	v_max_f32_e32 v2, v3, v2
	v_max_f32_e32 v3, v87, v87
	v_max_f32_e32 v4, v86, v86
	v_max_f32_e32 v3, v4, v3
	v_max3_f32 v3, v84, v85, v3
	v_max3_f32 v0, v0, v2, v3
	v_max_f32_e32 v2, v91, v91
	v_max_f32_e32 v3, v90, v90
	v_max_f32_e32 v2, v3, v2
	v_max_f32_e32 v3, v95, v95
	v_max_f32_e32 v4, v94, v94
	v_max_f32_e32 v3, v4, v3
	v_max3_f32 v2, v88, v89, v2
	v_max3_f32 v3, v92, v93, v3
	v_max3_f32 v0, v0, v2, v3
	v_mul_f32_e32 v0, 0x3e38aa3b, v0
	s_mov_b64 s[92:93], 0

; template <bool NA, bool FIXED> ...
;     ...
;       for (int ks = 0; ks < 4; ++ks) {
;         bf16x8 ak = *(const bf16x8*)(sk + s2 * 4096 + koff + (((ks * 2 + hl) ^ swk) << 4));
;         sc = __builtin_amdgcn_mfma_f32_32x32x16_bf16(ak, bq[ks], sc, 0, 0, 0);
;       }
;       const bool na_far = NA && latent && (s2 != (qcol0 >> 5));
;       if (na_far) {
;         const float* brow_ = btab + (tile - r + 7) * 31;
;         const int kcb = s2 * 32 + hl * 4;
;         if (qcol0 == 0) na_softmax<0, 4>(sc, o0, o1, mrun, lsum, brow_, kcb, w0, qcol, cs, lane);
;         else na_softmax<12, 16>(sc, o0, o1, mrun, lsum, brow_, kcb, w0, qcol, cs, lane);
;       } else {
;       if (!FIXED) {
;       float tmax;
;       if (NA && latent) {
;         const float* brow_ = btab + (tile - r + 7) * 31;
;         const int kcb = s2 * 32 + hl * 4;
; #pragma unroll
;         for (int i = 0; i < 16; ++i) {
;           int kc = kcb + 8 * (i >> 2) + (i & 3);
;           bool valid = (kc >= w0) && (kc < w0 + 16);
;           int dx = min(max(kc - qcol, -15), 15) + 15;
;           float bv = brow_[dx];
;           sc[i] = valid ? sc[i] * cs + bv : -1e30f;
;         }
;         tmax = fmaxf(fmaxf(sc[0], sc[1]), fmaxf(sc[2], sc[3]));
; #pragma unroll
;         for (int i = 4; i < 16; i += 4) tmax = fmaxf(tmax, fmaxf(fmaxf(sc[i], sc[i + 1]), fmaxf(sc[i + 2], sc[i + 3])));
;       } else {
;         tmax = fmaxf(fmaxf(sc[0], sc[1]), fmaxf(sc[2], sc[3]));
; #pragma unroll
;         for (int i = 4; i < 16; i += 4) tmax = fmaxf(tmax, fmaxf(fmaxf(sc[i], sc[i + 1]), fmaxf(sc[i + 2], sc[i + 3])));
;         tmax *= cs;
.LBB0_402:
	ds_read_b128 v[204:207], v201 offset:4096
	ds_read_b128 v[208:211], v198 offset:4096
	ds_read_b128 v[212:215], v200 offset:4096
	ds_read_b128 v[216:219], v199 offset:4096
	v_add_u32_e32 v196, s47, v138
	v_cvt_pk_bf16_f32 v10, v10, v11
	v_cvt_pk_bf16_f32 v11, v12, v13
	v_cvt_pk_bf16_f32 v12, v14, v15
	v_add_u32_e32 v14, v196, v149
	v_add_u32_e32 v18, v196, v150
	ds_read2st64_b64 v[14:17], v14 offset0:16 offset1:24
	ds_read2st64_b64 v[18:21], v18 offset0:16 offset1:24
	v_cvt_pk_bf16_f32 v13, v96, v97
	v_cvt_pk_bf16_f32 v8, v8, v9
	v_cvt_pk_bf16_f32 v9, v4, v5
	s_waitcnt lgkmcnt(0)
	v_mov_b32_e32 v22, v14
	v_mov_b32_e32 v23, v15
	v_mov_b32_e32 v24, v18
	v_mov_b32_e32 v25, v19
	v_mov_b32_e32 v18, v16
	v_mov_b32_e32 v19, v17
	v_mfma_f32_32x32x16_bf16 v[48:63], v[22:25], v[10:13], v[48:63]
	v_readlane_b32 s92, v252, 7
	v_readlane_b32 s93, v252, 8
	s_and_b64 s[92:93], s[92:93], s[16:17]
	s_mov_b64 s[16:17], -1
	s_and_b64 vcc, exec, s[92:93]
	v_mfma_f32_32x32x16_bf16 v[64:79], v[18:21], v[10:13], v[64:79]
	v_cvt_pk_bf16_f32 v10, v2, v3
	v_cvt_pk_bf16_f32 v11, v6, v7
	v_add_u32_e32 v2, v196, v151
	v_add_u32_e32 v6, v196, v152
	ds_read2st64_b64 v[2:5], v2 offset0:16 offset1:24
	ds_read2st64_b64 v[12:15], v6 offset0:16 offset1:24
	s_waitcnt lgkmcnt(0)
	v_mov_b32_e32 v16, v2
	v_mov_b32_e32 v17, v3
	v_mov_b32_e32 v18, v12
	v_mov_b32_e32 v19, v13
	v_mov_b32_e32 v12, v4
	v_mov_b32_e32 v13, v5
	s_waitcnt lgkmcnt(0)
	v_mfma_f32_32x32x16_bf16 v[80:95], v[204:207], v[112:115], 0
	s_waitcnt lgkmcnt(0)
	v_mfma_f32_32x32x16_bf16 v[80:95], v[208:211], v[116:119], v[80:95]
	s_waitcnt lgkmcnt(0)
	v_mfma_f32_32x32x16_bf16 v[80:95], v[212:215], v[120:123], v[80:95]
	v_mfma_f32_32x32x16_bf16 v[48:63], v[16:19], v[8:11], v[48:63]
	v_mfma_f32_32x32x16_bf16 v[64:79], v[12:15], v[8:11], v[64:79]
	s_waitcnt lgkmcnt(0)
	v_mfma_f32_32x32x16_bf16 v[80:95], v[216:219], v[124:127], v[80:95]
	s_cbranch_vccnz .LBB0_442
	s_andn2_b64 vcc, exec, s[96:97]
	s_cbranch_vccnz .LBB0_405
	s_nop 8
	v_max_f32_e32 v2, v81, v81
	v_max_f32_e32 v3, v80, v80
	v_max_f32_e32 v2, v3, v2
	v_max_f32_e32 v3, v83, v83
	v_max_f32_e32 v4, v82, v82
	v_max_f32_e32 v3, v4, v3
	v_max_f32_e32 v4, v87, v87
	v_max_f32_e32 v5, v86, v86
	v_max_f32_e32 v4, v5, v4
	v_max3_f32 v4, v84, v85, v4
	v_max3_f32 v2, v2, v3, v4
	v_max_f32_e32 v3, v91, v91
	v_max_f32_e32 v4, v90, v90
	v_max_f32_e32 v3, v4, v3
	v_max_f32_e32 v4, v95, v95
	v_max_f32_e32 v5, v94, v94
	v_max_f32_e32 v4, v5, v4
	v_max3_f32 v3, v88, v89, v3
	v_max3_f32 v4, v92, v93, v4
	v_max3_f32 v2, v2, v3, v4
	v_mul_f32_e32 v2, 0x3e38aa3b, v2
	s_mov_b64 s[16:17], 0
